# e23: P10 stagger classes aligned with the FNet halves (bid bit 7): the workgroups sharing a B' panel in an XCD's L2 run their GEMM units together
# baseline (speedup 1.0000x reference)
.LBB0_1586:
	s_cmp_lt_i32 s88, 11
	s_cselect_b64 s[18:19], -1, 0
	s_and_b64 s[0:1], s[18:19], s[0:1]
	s_andn2_b64 vcc, exec, s[0:1]
	s_cbranch_vccnz .LBB0_1596
	s_bitcmp1_b32 s2, 7
	s_cbranch_scc0 .Le22_gemm
	s_cmpk_gt_u32 s57, 0xfff
	s_cbranch_scc1 .Le22_gemm
	s_cmpk_eq_u32 s99, 0x7772
	s_cbranch_scc1 .Le22_gemm
	s_movk_i32 s99, 0x7771
	v_mov_b32_e32 v131, 0
	s_branch .Le22_fin
